# weight-conversion tiles (both instances): one 64-bit row address per tile, the other 15 by adding the uniform row stride; LDS read-back batched before the stores
# speedup vs baseline: 1.0257x; 1.0035x over previous
.LBB0_48:
	s_and_b64 vcc, exec, s[18:19]
	s_cbranch_vccz .LBB0_28
	v_add_u32_e32 v28, s11, v0
	s_ashr_i32 s11, s31, 1
	s_andn2_b32 s11, s11, 63
	v_add_u32_e32 v29, s11, v10
	s_lshr_b32 s11, s31, 1
	s_and_b32 s11, s11, 32
	v_or3_b32 v29, v29, s11, v11
	v_cndmask_b32_e64 v28, v28, v29, s[16:17]
	v_add_u32_e32 v29, s10, v1
	v_ashrrev_i32_e32 v30, 31, v29
	v_mul_lo_u32 v32, s14, v30
	v_mul_lo_u32 v33, s15, v29
	v_mad_u64_u32 v[30:31], s[16:17], s14, v29, 0
	v_add3_u32 v31, v31, v32, v33
	v_ashrrev_i32_e32 v29, 31, v28
	s_lshl_b64 s[44:45], s[14:15], 4
	s_waitcnt lgkmcnt(1)
	v_lshl_add_u64 v[30:31], v[30:31], 2, v[8:9]
	v_lshlrev_b64 v[28:29], 2, v[28:29]
	v_lshl_add_u64 v[30:31], v[30:31], 0, v[28:29]
	global_load_dword v46, v[30:31], off
	v_lshl_add_u64 v[32:33], v[30:31], 0, s[44:45]
	global_load_dword v47, v[32:33], off
	v_lshl_add_u64 v[30:31], v[32:33], 0, s[44:45]
	global_load_dword v48, v[30:31], off
	v_lshl_add_u64 v[32:33], v[30:31], 0, s[44:45]
	global_load_dword v49, v[32:33], off
	v_lshl_add_u64 v[30:31], v[32:33], 0, s[44:45]
	global_load_dword v50, v[30:31], off
	v_lshl_add_u64 v[32:33], v[30:31], 0, s[44:45]
	global_load_dword v51, v[32:33], off
	v_lshl_add_u64 v[30:31], v[32:33], 0, s[44:45]
	global_load_dword v52, v[30:31], off
	v_lshl_add_u64 v[32:33], v[30:31], 0, s[44:45]
	global_load_dword v53, v[32:33], off
	v_lshl_add_u64 v[30:31], v[32:33], 0, s[44:45]
	global_load_dword v28, v[30:31], off
	v_lshl_add_u64 v[32:33], v[30:31], 0, s[44:45]
	global_load_dword v29, v[32:33], off
	v_lshl_add_u64 v[30:31], v[32:33], 0, s[44:45]
	global_load_dword v44, v[30:31], off
	v_lshl_add_u64 v[32:33], v[30:31], 0, s[44:45]
	global_load_dword v45, v[32:33], off
	v_lshl_add_u64 v[30:31], v[32:33], 0, s[44:45]
	global_load_dword v54, v[30:31], off
	v_lshl_add_u64 v[32:33], v[30:31], 0, s[44:45]
	global_load_dword v55, v[32:33], off
	v_lshl_add_u64 v[30:31], v[32:33], 0, s[44:45]
	global_load_dword v56, v[30:31], off
	v_lshl_add_u64 v[32:33], v[30:31], 0, s[44:45]
	global_load_dword v57, v[32:33], off
	s_waitcnt vmcnt(15)
	ds_write_b32 v4, v46
	s_waitcnt vmcnt(14)
	ds_write_b32 v4, v47 offset:1040
	s_waitcnt vmcnt(13)
	ds_write_b32 v4, v48 offset:2080
	s_waitcnt vmcnt(12)
	ds_write_b32 v4, v49 offset:3120
	s_waitcnt vmcnt(11)
	ds_write_b32 v4, v50 offset:4160
	s_waitcnt vmcnt(10)
	ds_write_b32 v4, v51 offset:5200
	s_waitcnt vmcnt(9)
	ds_write_b32 v4, v52 offset:6240
	s_waitcnt vmcnt(8)
	ds_write_b32 v4, v53 offset:7280
	s_waitcnt vmcnt(7)
	ds_write_b32 v4, v28 offset:8320
	s_waitcnt vmcnt(6)
	ds_write_b32 v4, v29 offset:9360
	s_waitcnt vmcnt(5)
	ds_write_b32 v4, v44 offset:10400
	s_waitcnt vmcnt(4)
	ds_write_b32 v4, v45 offset:11440
	s_waitcnt vmcnt(3)
	ds_write_b32 v4, v54 offset:12480
	s_waitcnt vmcnt(2)
	ds_write_b32 v4, v55 offset:13520
	s_waitcnt vmcnt(1)
	ds_write_b32 v4, v56 offset:14560
	s_waitcnt vmcnt(0)
	ds_write_b32 v4, v57 offset:15600
	s_waitcnt lgkmcnt(0)
	s_barrier
	ds_read2_b32 v[30:31], v27 offset1:4
	ds_read2_b32 v[32:33], v27 offset0:8 offset1:12
	ds_read2_b32 v[34:35], v27 offset0:16 offset1:20
	ds_read2_b32 v[36:37], v27 offset0:24 offset1:28
	ds_read2_b32 v[38:39], v27 offset0:32 offset1:36
	ds_read2_b32 v[40:41], v27 offset0:40 offset1:44
	ds_read2_b32 v[42:43], v27 offset0:48 offset1:52
	ds_read2_b32 v[44:45], v27 offset0:56 offset1:60
	s_ashr_i32 s11, s10, 31
	s_lshl_b64 s[10:11], s[10:11], 1
	v_lshl_add_u64 v[6:7], v[6:7], 0, s[10:11]
	v_lshl_add_u64 v[6:7], v[6:7], 0, v[2:3]
	v_add_u32_e32 v46, s31, v1
	v_ashrrev_i32_e32 v47, 31, v46
	v_mul_lo_u32 v48, s8, v47
	v_mul_lo_u32 v49, s9, v46
	v_mad_u64_u32 v[46:47], s[10:11], s8, v46, 0
	v_add3_u32 v47, v47, v48, v49
	s_lshl_b64 s[46:47], s[8:9], 3
	v_lshl_add_u64 v[46:47], v[46:47], 1, v[6:7]
	s_waitcnt lgkmcnt(7)
	v_bfe_u32 v50, v30, 16, 1
	v_add3_u32 v50, v30, v50, s30
	global_store_short_d16_hi v[46:47], v50, off
	v_lshl_add_u64 v[48:49], v[46:47], 0, s[46:47]
	v_bfe_u32 v51, v31, 16, 1
	v_add3_u32 v51, v31, v51, s30
	global_store_short_d16_hi v[48:49], v51, off
	v_lshl_add_u64 v[46:47], v[48:49], 0, s[46:47]
	s_waitcnt lgkmcnt(6)
	v_bfe_u32 v50, v32, 16, 1
	v_add3_u32 v50, v32, v50, s30
	global_store_short_d16_hi v[46:47], v50, off
	v_lshl_add_u64 v[48:49], v[46:47], 0, s[46:47]
	v_bfe_u32 v51, v33, 16, 1
	v_add3_u32 v51, v33, v51, s30
	global_store_short_d16_hi v[48:49], v51, off
	v_lshl_add_u64 v[46:47], v[48:49], 0, s[46:47]
	s_waitcnt lgkmcnt(5)
	v_bfe_u32 v50, v34, 16, 1
	v_add3_u32 v50, v34, v50, s30
	global_store_short_d16_hi v[46:47], v50, off
	v_lshl_add_u64 v[48:49], v[46:47], 0, s[46:47]
	v_bfe_u32 v51, v35, 16, 1
	v_add3_u32 v51, v35, v51, s30
	global_store_short_d16_hi v[48:49], v51, off
	v_lshl_add_u64 v[46:47], v[48:49], 0, s[46:47]
	s_waitcnt lgkmcnt(4)
	v_bfe_u32 v50, v36, 16, 1
	v_add3_u32 v50, v36, v50, s30
	global_store_short_d16_hi v[46:47], v50, off
	v_lshl_add_u64 v[48:49], v[46:47], 0, s[46:47]
	v_bfe_u32 v51, v37, 16, 1
	v_add3_u32 v51, v37, v51, s30
	global_store_short_d16_hi v[48:49], v51, off
	v_lshl_add_u64 v[46:47], v[48:49], 0, s[46:47]
	s_waitcnt lgkmcnt(3)
	v_bfe_u32 v50, v38, 16, 1
	v_add3_u32 v50, v38, v50, s30
	global_store_short_d16_hi v[46:47], v50, off
	v_lshl_add_u64 v[48:49], v[46:47], 0, s[46:47]
	v_bfe_u32 v51, v39, 16, 1
	v_add3_u32 v51, v39, v51, s30
	global_store_short_d16_hi v[48:49], v51, off
	v_lshl_add_u64 v[46:47], v[48:49], 0, s[46:47]
	s_waitcnt lgkmcnt(2)
	v_bfe_u32 v50, v40, 16, 1
	v_add3_u32 v50, v40, v50, s30
	global_store_short_d16_hi v[46:47], v50, off
	v_lshl_add_u64 v[48:49], v[46:47], 0, s[46:47]
	v_bfe_u32 v51, v41, 16, 1
	v_add3_u32 v51, v41, v51, s30
	global_store_short_d16_hi v[48:49], v51, off
	v_lshl_add_u64 v[46:47], v[48:49], 0, s[46:47]
	s_waitcnt lgkmcnt(1)
	v_bfe_u32 v50, v42, 16, 1
	v_add3_u32 v50, v42, v50, s30
	global_store_short_d16_hi v[46:47], v50, off
	v_lshl_add_u64 v[48:49], v[46:47], 0, s[46:47]
	v_bfe_u32 v51, v43, 16, 1
	v_add3_u32 v51, v43, v51, s30
	global_store_short_d16_hi v[48:49], v51, off
	v_lshl_add_u64 v[46:47], v[48:49], 0, s[46:47]
	s_waitcnt lgkmcnt(0)
	v_bfe_u32 v50, v44, 16, 1
	v_add3_u32 v50, v44, v50, s30
	global_store_short_d16_hi v[46:47], v50, off
	v_lshl_add_u64 v[48:49], v[46:47], 0, s[46:47]
	v_bfe_u32 v51, v45, 16, 1
	v_add3_u32 v51, v45, v51, s30
	global_store_short_d16_hi v[48:49], v51, off
	s_barrier
	s_branch .LBB0_28

.LBB0_248:
	v_add_u32_e32 v70, s17, v1
	s_mov_b64 s[10:11], -1
	s_andn2_b64 vcc, exec, s[8:9]
	v_ashrrev_i32_e32 v76, 31, v70
	v_mul_lo_u32 v75, s1, v70
	s_cbranch_vccz .LBB0_250
	v_add_u32_e32 v67, s17, v14
	v_add_u32_e32 v66, s17, v15
	v_add_u32_e32 v65, s17, v16
	v_add_u32_e32 v60, s17, v17
	v_add_u32_e32 v59, s17, v18
	v_add_u32_e32 v54, s17, v19
	v_add_u32_e32 v53, s17, v20
	v_add_u32_e32 v48, s17, v21
	v_add_u32_e32 v47, s17, v22
	v_add_u32_e32 v42, s17, v23
	v_add_u32_e32 v41, s17, v24
	v_add_u32_e32 v36, s17, v25
	v_add_u32_e32 v35, s17, v26
	v_add_u32_e32 v30, s17, v27
	v_add_u32_e32 v29, s17, v28
	v_ashrrev_i32_e32 v74, 31, v67
	v_mul_lo_u32 v73, s1, v67
	v_ashrrev_i32_e32 v72, 31, v66
	v_mul_lo_u32 v71, s1, v66
	v_ashrrev_i32_e32 v69, 31, v65
	v_mul_lo_u32 v68, s1, v65
	v_ashrrev_i32_e32 v64, 31, v60
	v_mul_lo_u32 v63, s1, v60
	v_ashrrev_i32_e32 v62, 31, v59
	v_mul_lo_u32 v61, s1, v59
	v_ashrrev_i32_e32 v58, 31, v54
	v_mul_lo_u32 v57, s1, v54
	v_ashrrev_i32_e32 v56, 31, v53
	v_mul_lo_u32 v55, s1, v53
	v_ashrrev_i32_e32 v52, 31, v48
	v_mul_lo_u32 v51, s1, v48
	v_ashrrev_i32_e32 v50, 31, v47
	v_mul_lo_u32 v49, s1, v47
	v_ashrrev_i32_e32 v46, 31, v42
	v_mul_lo_u32 v45, s1, v42
	v_ashrrev_i32_e32 v44, 31, v41
	v_mul_lo_u32 v43, s1, v41
	v_ashrrev_i32_e32 v40, 31, v36
	v_mul_lo_u32 v39, s1, v36
	v_ashrrev_i32_e32 v38, 31, v35
	v_mul_lo_u32 v37, s1, v35
	v_ashrrev_i32_e32 v34, 31, v30
	v_mul_lo_u32 v33, s1, v30
	v_ashrrev_i32_e32 v32, 31, v29
	v_mul_lo_u32 v31, s1, v29
	ds_read_b64 v[8:9], v229 offset:63760
	s_ashr_i32 s3, s2, 31
	s_add_i32 s1, s17, 0xfffffa00
	s_lshl_b64 s[8:9], s[2:3], 1
	v_add_u32_e32 v78, s1, v1
	s_waitcnt lgkmcnt(0)
	v_lshl_add_u64 v[8:9], v[8:9], 0, s[8:9]
	v_lshl_add_u64 v[8:9], v[8:9], 0, v[228:229]
	s_mov_b64 s[10:11], 0xf1d4000
	v_ashrrev_i32_e32 v79, 31, v78
	v_lshl_add_u64 v[10:11], v[8:9], 0, s[10:11]
	v_lshlrev_b64 v[78:79], 11, v[78:79]
	v_lshl_add_u64 v[78:79], v[10:11], 0, v[78:79]
	global_load_ushort v110, v[78:79], off
	v_lshl_add_u64 v[8:9], v[4:5], 0, s[8:9]
	v_mul_lo_u32 v80, s0, v76
	v_mad_u64_u32 v[126:127], s[8:9], s0, v70, 0
	v_lshl_add_u64 v[8:9], v[8:9], 0, v[228:229]
	v_add3_u32 v127, v127, v80, v75
	v_lshl_add_u64 v[126:127], v[126:127], 1, v[8:9]
	v_mul_lo_u32 v80, s0, v74
	s_mov_b64 s[10:11], 0
	v_add_u32_e32 v78, s1, v14
	v_ashrrev_i32_e32 v79, 31, v78
	v_lshlrev_b64 v[78:79], 11, v[78:79]
	v_lshl_add_u64 v[78:79], v[10:11], 0, v[78:79]
	global_load_ushort v111, v[78:79], off
	v_mad_u64_u32 v[128:129], s[8:9], s0, v67, 0
	v_add3_u32 v129, v129, v80, v73
	v_lshl_add_u64 v[128:129], v[128:129], 1, v[8:9]
	v_mul_lo_u32 v80, s0, v72
	v_add_u32_e32 v78, s1, v15
	v_ashrrev_i32_e32 v79, 31, v78
	v_lshlrev_b64 v[78:79], 11, v[78:79]
	v_lshl_add_u64 v[78:79], v[10:11], 0, v[78:79]
	global_load_ushort v112, v[78:79], off
	v_mad_u64_u32 v[130:131], s[8:9], s0, v66, 0
	v_add3_u32 v131, v131, v80, v71
	v_lshl_add_u64 v[130:131], v[130:131], 1, v[8:9]
	v_mul_lo_u32 v80, s0, v69
	v_add_u32_e32 v78, s1, v16
	v_ashrrev_i32_e32 v79, 31, v78
	v_lshlrev_b64 v[78:79], 11, v[78:79]
	v_lshl_add_u64 v[78:79], v[10:11], 0, v[78:79]
	global_load_ushort v113, v[78:79], off
	v_mad_u64_u32 v[132:133], s[8:9], s0, v65, 0
	v_add3_u32 v133, v133, v80, v68
	v_lshl_add_u64 v[132:133], v[132:133], 1, v[8:9]
	v_mul_lo_u32 v80, s0, v64
	v_add_u32_e32 v78, s1, v17
	v_ashrrev_i32_e32 v79, 31, v78
	v_lshlrev_b64 v[78:79], 11, v[78:79]
	v_lshl_add_u64 v[78:79], v[10:11], 0, v[78:79]
	global_load_ushort v114, v[78:79], off
	v_mad_u64_u32 v[134:135], s[8:9], s0, v60, 0
	v_add3_u32 v135, v135, v80, v63
	v_lshl_add_u64 v[134:135], v[134:135], 1, v[8:9]
	v_mul_lo_u32 v80, s0, v62
	v_add_u32_e32 v78, s1, v18
	v_ashrrev_i32_e32 v79, 31, v78
	v_lshlrev_b64 v[78:79], 11, v[78:79]
	v_lshl_add_u64 v[78:79], v[10:11], 0, v[78:79]
	global_load_ushort v115, v[78:79], off
	v_mad_u64_u32 v[136:137], s[8:9], s0, v59, 0
	v_add3_u32 v137, v137, v80, v61
	v_lshl_add_u64 v[136:137], v[136:137], 1, v[8:9]
	v_mul_lo_u32 v80, s0, v58
	v_add_u32_e32 v78, s1, v19
	v_ashrrev_i32_e32 v79, 31, v78
	v_lshlrev_b64 v[78:79], 11, v[78:79]
	v_lshl_add_u64 v[78:79], v[10:11], 0, v[78:79]
	global_load_ushort v116, v[78:79], off
	v_mad_u64_u32 v[138:139], s[8:9], s0, v54, 0
	v_add3_u32 v139, v139, v80, v57
	v_lshl_add_u64 v[138:139], v[138:139], 1, v[8:9]
	v_mul_lo_u32 v80, s0, v56
	v_add_u32_e32 v78, s1, v20
	v_ashrrev_i32_e32 v79, 31, v78
	v_lshlrev_b64 v[78:79], 11, v[78:79]
	v_lshl_add_u64 v[78:79], v[10:11], 0, v[78:79]
	global_load_ushort v117, v[78:79], off
	v_mad_u64_u32 v[140:141], s[8:9], s0, v53, 0
	v_add3_u32 v141, v141, v80, v55
	v_lshl_add_u64 v[140:141], v[140:141], 1, v[8:9]
	v_mul_lo_u32 v80, s0, v52
	v_add_u32_e32 v78, s1, v21
	v_ashrrev_i32_e32 v79, 31, v78
	v_lshlrev_b64 v[78:79], 11, v[78:79]
	v_lshl_add_u64 v[78:79], v[10:11], 0, v[78:79]
	global_load_ushort v118, v[78:79], off
	v_mad_u64_u32 v[142:143], s[8:9], s0, v48, 0
	v_add3_u32 v143, v143, v80, v51
	v_lshl_add_u64 v[142:143], v[142:143], 1, v[8:9]
	v_mul_lo_u32 v80, s0, v50
	v_add_u32_e32 v78, s1, v22
	v_ashrrev_i32_e32 v79, 31, v78
	v_lshlrev_b64 v[78:79], 11, v[78:79]
	v_lshl_add_u64 v[78:79], v[10:11], 0, v[78:79]
	global_load_ushort v119, v[78:79], off
	v_mad_u64_u32 v[144:145], s[8:9], s0, v47, 0
	v_add3_u32 v145, v145, v80, v49
	v_lshl_add_u64 v[144:145], v[144:145], 1, v[8:9]
	v_mul_lo_u32 v80, s0, v46
	v_add_u32_e32 v78, s1, v23
	v_ashrrev_i32_e32 v79, 31, v78
	v_lshlrev_b64 v[78:79], 11, v[78:79]
	v_lshl_add_u64 v[78:79], v[10:11], 0, v[78:79]
	global_load_ushort v120, v[78:79], off
	v_mad_u64_u32 v[146:147], s[8:9], s0, v42, 0
	v_add3_u32 v147, v147, v80, v45
	v_lshl_add_u64 v[146:147], v[146:147], 1, v[8:9]
	v_mul_lo_u32 v80, s0, v44
	v_add_u32_e32 v78, s1, v24
	v_ashrrev_i32_e32 v79, 31, v78
	v_lshlrev_b64 v[78:79], 11, v[78:79]
	v_lshl_add_u64 v[78:79], v[10:11], 0, v[78:79]
	global_load_ushort v121, v[78:79], off
	v_mad_u64_u32 v[148:149], s[8:9], s0, v41, 0
	v_add3_u32 v149, v149, v80, v43
	v_lshl_add_u64 v[148:149], v[148:149], 1, v[8:9]
	v_mul_lo_u32 v80, s0, v40
	v_add_u32_e32 v78, s1, v25
	v_ashrrev_i32_e32 v79, 31, v78
	v_lshlrev_b64 v[78:79], 11, v[78:79]
	v_lshl_add_u64 v[78:79], v[10:11], 0, v[78:79]
	global_load_ushort v122, v[78:79], off
	v_mad_u64_u32 v[150:151], s[8:9], s0, v36, 0
	v_add3_u32 v151, v151, v80, v39
	v_lshl_add_u64 v[150:151], v[150:151], 1, v[8:9]
	v_mul_lo_u32 v80, s0, v38
	v_add_u32_e32 v78, s1, v26
	v_ashrrev_i32_e32 v79, 31, v78
	v_lshlrev_b64 v[78:79], 11, v[78:79]
	v_lshl_add_u64 v[78:79], v[10:11], 0, v[78:79]
	global_load_ushort v123, v[78:79], off
	v_mad_u64_u32 v[152:153], s[8:9], s0, v35, 0
	v_add3_u32 v153, v153, v80, v37
	v_lshl_add_u64 v[152:153], v[152:153], 1, v[8:9]
	v_mul_lo_u32 v80, s0, v34
	v_add_u32_e32 v78, s1, v27
	v_ashrrev_i32_e32 v79, 31, v78
	v_lshlrev_b64 v[78:79], 11, v[78:79]
	v_lshl_add_u64 v[78:79], v[10:11], 0, v[78:79]
	global_load_ushort v124, v[78:79], off
	v_mad_u64_u32 v[154:155], s[8:9], s0, v30, 0
	v_add3_u32 v155, v155, v80, v33
	v_lshl_add_u64 v[154:155], v[154:155], 1, v[8:9]
	v_add_u32_e32 v78, s1, v28
	v_ashrrev_i32_e32 v79, 31, v78
	v_lshlrev_b64 v[78:79], 11, v[78:79]
	v_lshl_add_u64 v[10:11], v[10:11], 0, v[78:79]
	global_load_ushort v125, v[10:11], off
	v_mul_lo_u32 v78, s0, v32
	v_mad_u64_u32 v[10:11], s[8:9], s0, v29, 0
	v_add3_u32 v11, v11, v78, v31
	v_lshl_add_u64 v[156:157], v[10:11], 1, v[8:9]
	s_waitcnt vmcnt(0)
	global_store_short v[126:127], v110, off
	global_store_short v[128:129], v111, off
	global_store_short v[130:131], v112, off
	global_store_short v[132:133], v113, off
	global_store_short v[134:135], v114, off
	global_store_short v[136:137], v115, off
	global_store_short v[138:139], v116, off
	global_store_short v[140:141], v117, off
	global_store_short v[142:143], v118, off
	global_store_short v[144:145], v119, off
	global_store_short v[146:147], v120, off
	global_store_short v[148:149], v121, off
	global_store_short v[150:151], v122, off
	global_store_short v[152:153], v123, off
	global_store_short v[154:155], v124, off
	global_store_short v[156:157], v125, off
	s_barrier
.LBB0_250:
	s_andn2_b64 vcc, exec, s[10:11]
	s_cbranch_vccnz .LBB0_226
	s_ashr_i32 s1, s17, 1
	s_andn2_b32 s1, s1, 63
	v_add_u32_e32 v9, s1, v12
	s_lshr_b32 s1, s17, 1
	s_and_b32 s1, s1, 32
	v_add_u32_e32 v8, s16, v0
	v_or3_b32 v9, v9, s1, v13
	v_cndmask_b32_e64 v8, v8, v9, s[6:7]
	v_add_u32_e32 v9, s2, v1
	v_ashrrev_i32_e32 v10, 31, v9
	v_mul_lo_u32 v77, s4, v10
	v_mul_lo_u32 v78, s5, v9
	v_mad_u64_u32 v[10:11], s[6:7], s4, v9, 0
	v_add3_u32 v11, v11, v77, v78
	v_ashrrev_i32_e32 v9, 31, v8
	s_lshl_b64 s[44:45], s[4:5], 4
	v_lshl_add_u64 v[10:11], v[10:11], 2, v[6:7]
	v_lshlrev_b64 v[8:9], 2, v[8:9]
	v_lshl_add_u64 v[10:11], v[10:11], 0, v[8:9]
	global_load_dword v110, v[10:11], off
	v_lshl_add_u64 v[6:7], v[10:11], 0, s[44:45]
	global_load_dword v111, v[6:7], off
	v_lshl_add_u64 v[10:11], v[6:7], 0, s[44:45]
	global_load_dword v112, v[10:11], off
	v_lshl_add_u64 v[6:7], v[10:11], 0, s[44:45]
	global_load_dword v113, v[6:7], off
	v_lshl_add_u64 v[10:11], v[6:7], 0, s[44:45]
	global_load_dword v114, v[10:11], off
	v_lshl_add_u64 v[6:7], v[10:11], 0, s[44:45]
	global_load_dword v115, v[6:7], off
	v_lshl_add_u64 v[10:11], v[6:7], 0, s[44:45]
	global_load_dword v116, v[10:11], off
	v_lshl_add_u64 v[6:7], v[10:11], 0, s[44:45]
	global_load_dword v117, v[6:7], off
	v_lshl_add_u64 v[10:11], v[6:7], 0, s[44:45]
	global_load_dword v118, v[10:11], off
	v_lshl_add_u64 v[6:7], v[10:11], 0, s[44:45]
	global_load_dword v119, v[6:7], off
	v_lshl_add_u64 v[10:11], v[6:7], 0, s[44:45]
	global_load_dword v120, v[10:11], off
	v_lshl_add_u64 v[6:7], v[10:11], 0, s[44:45]
	global_load_dword v121, v[6:7], off
	v_lshl_add_u64 v[10:11], v[6:7], 0, s[44:45]
	global_load_dword v122, v[10:11], off
	v_lshl_add_u64 v[6:7], v[10:11], 0, s[44:45]
	global_load_dword v123, v[6:7], off
	v_lshl_add_u64 v[10:11], v[6:7], 0, s[44:45]
	global_load_dword v124, v[10:11], off
	v_lshl_add_u64 v[6:7], v[10:11], 0, s[44:45]
	global_load_dword v125, v[6:7], off
	s_ashr_i32 s3, s2, 31
	s_lshl_b64 s[2:3], s[2:3], 1
	v_lshl_add_u64 v[4:5], v[4:5], 0, s[2:3]
	v_lshl_add_u64 v[4:5], v[4:5], 0, v[228:229]
	v_mul_lo_u32 v76, s0, v76
	s_waitcnt vmcnt(0)
	ds_write_b32 v2, v110
	ds_write_b32 v2, v111 offset:1040
	ds_write_b32 v2, v112 offset:2080
	ds_write_b32 v2, v113 offset:3120
	ds_write_b32 v2, v114 offset:4160
	ds_write_b32 v2, v115 offset:5200
	ds_write_b32 v2, v116 offset:6240
	ds_write_b32 v2, v117 offset:7280
	ds_write_b32 v2, v118 offset:8320
	ds_write_b32 v2, v119 offset:9360
	ds_write_b32 v2, v120 offset:10400
	ds_write_b32 v2, v121 offset:11440
	ds_write_b32 v2, v122 offset:12480
	ds_write_b32 v2, v123 offset:13520
	ds_write_b32 v2, v124 offset:14560
	ds_write_b32 v2, v125 offset:15600
	s_waitcnt lgkmcnt(0)
	s_barrier
	ds_read2_b32 v[30:31], v3 offset1:4
	ds_read2_b32 v[32:33], v3 offset0:8 offset1:12
	ds_read2_b32 v[34:35], v3 offset0:16 offset1:20
	ds_read2_b32 v[36:37], v3 offset0:24 offset1:28
	ds_read2_b32 v[38:39], v3 offset0:32 offset1:36
	ds_read2_b32 v[40:41], v3 offset0:40 offset1:44
	ds_read2_b32 v[42:43], v3 offset0:48 offset1:52
	ds_read2_b32 v[44:45], v3 offset0:56 offset1:60
	v_mad_u64_u32 v[10:11], s[2:3], s0, v70, 0
	v_add3_u32 v11, v11, v76, v75
	s_lshl_b32 s46, s0, 3
	s_mov_b32 s47, 0
	v_lshl_add_u64 v[10:11], v[10:11], 1, v[4:5]
	s_waitcnt lgkmcnt(7)
	v_bfe_u32 v8, v30, 16, 1
	v_add3_u32 v8, v30, v8, s89
	global_store_short_d16_hi v[10:11], v8, off
	v_lshl_add_u64 v[6:7], v[10:11], 0, s[46:47]
	v_bfe_u32 v9, v31, 16, 1
	v_add3_u32 v9, v31, v9, s89
	global_store_short_d16_hi v[6:7], v9, off
	v_lshl_add_u64 v[10:11], v[6:7], 0, s[46:47]
	s_waitcnt lgkmcnt(6)
	v_bfe_u32 v8, v32, 16, 1
	v_add3_u32 v8, v32, v8, s89
	global_store_short_d16_hi v[10:11], v8, off
	v_lshl_add_u64 v[6:7], v[10:11], 0, s[46:47]
	v_bfe_u32 v9, v33, 16, 1
	v_add3_u32 v9, v33, v9, s89
	global_store_short_d16_hi v[6:7], v9, off
	v_lshl_add_u64 v[10:11], v[6:7], 0, s[46:47]
	s_waitcnt lgkmcnt(5)
	v_bfe_u32 v8, v34, 16, 1
	v_add3_u32 v8, v34, v8, s89
	global_store_short_d16_hi v[10:11], v8, off
	v_lshl_add_u64 v[6:7], v[10:11], 0, s[46:47]
	v_bfe_u32 v9, v35, 16, 1
	v_add3_u32 v9, v35, v9, s89
	global_store_short_d16_hi v[6:7], v9, off
	v_lshl_add_u64 v[10:11], v[6:7], 0, s[46:47]
	s_waitcnt lgkmcnt(4)
	v_bfe_u32 v8, v36, 16, 1
	v_add3_u32 v8, v36, v8, s89
	global_store_short_d16_hi v[10:11], v8, off
	v_lshl_add_u64 v[6:7], v[10:11], 0, s[46:47]
	v_bfe_u32 v9, v37, 16, 1
	v_add3_u32 v9, v37, v9, s89
	global_store_short_d16_hi v[6:7], v9, off
	v_lshl_add_u64 v[10:11], v[6:7], 0, s[46:47]
	s_waitcnt lgkmcnt(3)
	v_bfe_u32 v8, v38, 16, 1
	v_add3_u32 v8, v38, v8, s89
	global_store_short_d16_hi v[10:11], v8, off
	v_lshl_add_u64 v[6:7], v[10:11], 0, s[46:47]
	v_bfe_u32 v9, v39, 16, 1
	v_add3_u32 v9, v39, v9, s89
	global_store_short_d16_hi v[6:7], v9, off
	v_lshl_add_u64 v[10:11], v[6:7], 0, s[46:47]
	s_waitcnt lgkmcnt(2)
	v_bfe_u32 v8, v40, 16, 1
	v_add3_u32 v8, v40, v8, s89
	global_store_short_d16_hi v[10:11], v8, off
	v_lshl_add_u64 v[6:7], v[10:11], 0, s[46:47]
	v_bfe_u32 v9, v41, 16, 1
	v_add3_u32 v9, v41, v9, s89
	global_store_short_d16_hi v[6:7], v9, off
	v_lshl_add_u64 v[10:11], v[6:7], 0, s[46:47]
	s_waitcnt lgkmcnt(1)
	v_bfe_u32 v8, v42, 16, 1
	v_add3_u32 v8, v42, v8, s89
	global_store_short_d16_hi v[10:11], v8, off
	v_lshl_add_u64 v[6:7], v[10:11], 0, s[46:47]
	v_bfe_u32 v9, v43, 16, 1
	v_add3_u32 v9, v43, v9, s89
	global_store_short_d16_hi v[6:7], v9, off
	v_lshl_add_u64 v[10:11], v[6:7], 0, s[46:47]
	s_waitcnt lgkmcnt(0)
	v_bfe_u32 v8, v44, 16, 1
	v_add3_u32 v8, v44, v8, s89
	global_store_short_d16_hi v[10:11], v8, off
	v_lshl_add_u64 v[6:7], v[10:11], 0, s[46:47]
	v_bfe_u32 v9, v45, 16, 1
	v_add3_u32 v9, v45, v9, s89
	global_store_short_d16_hi v[6:7], v9, off
	s_barrier
	s_branch .LBB0_226
